# LDS-DMA attention staging: buffer-flip of the fragment address registers woven into the MFMA gaps instead of a block before the barrier
# speedup vs baseline: 1.0101x; 1.0035x over previous
.Lattn_nf_loop:
	ds_read_b128 v[98:101], v82 offset:0
	ds_read_b128 v[102:105], v83 offset:0
	ds_read_b128 v[106:109], v84 offset:0
	ds_read_b128 v[110:113], v85 offset:0
	s_and_b32 s10, s15, 1
	s_xor_b32 s10, s10, 1
	s_lshl_b32 s10, s10, 15
	s_add_i32 s10, s10, s11
	s_add_i32 s6, s10, 0x10000
	s_waitcnt lgkmcnt(3)
	v_mfma_f32_32x32x16_bf16 v[138:153], v[98:101], v[10:13], 0
	ds_read_b128 v[98:101], v82 offset:8192
	s_add_i32 m0, s10, 0x0
	s_nop 0
	global_load_lds_dwordx4 v124, s[64:65]
	s_add_i32 m0, s10, 0x2000
	s_nop 0
	global_load_lds_dwordx4 v124, s[66:67]
	s_waitcnt lgkmcnt(3)
	v_mfma_f32_32x32x16_bf16 v[138:153], v[102:105], v[14:17], v[138:153]
	ds_read_b128 v[102:105], v83 offset:8192
	s_add_i32 m0, s10, 0x4000
	s_nop 0
	global_load_lds_dwordx4 v124, s[68:69]
	s_add_i32 m0, s10, 0x6000
	s_nop 0
	global_load_lds_dwordx4 v124, s[70:71]
	v_add_u32_e32 v124, s36, v124
	s_waitcnt lgkmcnt(3)
	v_mfma_f32_32x32x16_bf16 v[138:153], v[106:109], v[2:5], v[138:153]
	ds_read_b128 v[106:109], v84 offset:8192
	s_add_i32 m0, s6, 0x0
	s_nop 0
	global_load_lds_dwordx4 v125, s[72:73]
	s_add_i32 m0, s6, 0x2000
	s_nop 0
	global_load_lds_dwordx4 v125, s[74:75]
	s_waitcnt lgkmcnt(3)
	v_mfma_f32_32x32x16_bf16 v[138:153], v[110:113], v[6:9], v[138:153]
	ds_read_b128 v[110:113], v85 offset:8192
	s_add_i32 m0, s6, 0x4000
	s_nop 0
	global_load_lds_dwordx4 v125, s[76:77]
	s_add_i32 m0, s6, 0x6000
	s_nop 0
	global_load_lds_dwordx4 v125, s[78:79]
	v_add_u32_e32 v125, s38, v125
	ds_read_b128 v[128:131], v86 offset:0
	ds_read_b128 v[184:187], v86 offset:8192
	ds_read_b128 v[188:191], v86 offset:16384
	ds_read_b128 v[192:195], v86 offset:24576
	s_waitcnt lgkmcnt(7)
	v_mfma_f32_32x32x16_bf16 v[154:169], v[98:101], v[10:13], 0
	ds_read_b128 v[98:101], v82 offset:16384
	v_exp_f32_e32 v138, v138
	v_exp_f32_e32 v139, v139
	v_exp_f32_e32 v140, v140
	v_exp_f32_e32 v141, v141
	v_exp_f32_e32 v142, v142
	v_exp_f32_e32 v143, v143
	s_waitcnt lgkmcnt(7)
	v_mfma_f32_32x32x16_bf16 v[154:169], v[102:105], v[14:17], v[154:169]
	ds_read_b128 v[102:105], v83 offset:16384
	v_exp_f32_e32 v144, v144
	v_exp_f32_e32 v145, v145
	v_add_f32_e32 v122, v138, v122
	v_add_f32_e32 v122, v139, v122
	v_add_f32_e32 v122, v140, v122
	v_add_f32_e32 v122, v141, v122
	v_add_f32_e32 v122, v142, v122
	v_add_f32_e32 v122, v143, v122
	v_add_f32_e32 v122, v144, v122
	v_add_f32_e32 v122, v145, v122
	v_cvt_pk_bf16_f32 v114, v138, v139
	v_cvt_pk_bf16_f32 v115, v140, v141
	v_cvt_pk_bf16_f32 v116, v142, v143
	v_cvt_pk_bf16_f32 v117, v144, v145
	ds_read_b128 v[196:199], v87 offset:0
	ds_read_b128 v[216:219], v87 offset:8192
	ds_read_b128 v[200:203], v87 offset:16384
	ds_read_b128 v[204:207], v87 offset:24576
	s_waitcnt lgkmcnt(11)
	v_mfma_f32_32x32x16_bf16 v[154:169], v[106:109], v[2:5], v[154:169]
	ds_read_b128 v[106:109], v84 offset:16384
	v_exp_f32_e32 v146, v146
	v_exp_f32_e32 v147, v147
	s_waitcnt lgkmcnt(11)
	v_mfma_f32_32x32x16_bf16 v[154:169], v[110:113], v[6:9], v[154:169]
	ds_read_b128 v[110:113], v85 offset:16384
	v_exp_f32_e32 v148, v148
	v_exp_f32_e32 v149, v149
	s_waitcnt lgkmcnt(11)
	v_mfma_f32_32x32x16_bf16 v[18:33], v[128:131], v[114:117], v[18:33]
	v_exp_f32_e32 v150, v150
	v_exp_f32_e32 v151, v151
	s_waitcnt lgkmcnt(10)
	v_mfma_f32_32x32x16_bf16 v[34:49], v[184:187], v[114:117], v[34:49]
	v_exp_f32_e32 v152, v152
	v_exp_f32_e32 v153, v153
	s_waitcnt lgkmcnt(9)
	v_mfma_f32_32x32x16_bf16 v[50:65], v[188:191], v[114:117], v[50:65]
	v_add_f32_e32 v122, v146, v122
	v_add_f32_e32 v122, v147, v122
	v_add_f32_e32 v122, v148, v122
	v_add_f32_e32 v122, v149, v122
	s_waitcnt lgkmcnt(8)
	v_mfma_f32_32x32x16_bf16 v[66:81], v[192:195], v[114:117], v[66:81]
	v_add_f32_e32 v122, v150, v122
	v_add_f32_e32 v122, v151, v122
	v_add_f32_e32 v122, v152, v122
	v_add_f32_e32 v122, v153, v122
	v_cvt_pk_bf16_f32 v118, v146, v147
	v_cvt_pk_bf16_f32 v119, v148, v149
	v_cvt_pk_bf16_f32 v120, v150, v151
	v_cvt_pk_bf16_f32 v121, v152, v153
	ds_read_b128 v[128:131], v88 offset:0
	ds_read_b128 v[184:187], v88 offset:8192
	ds_read_b128 v[188:191], v88 offset:16384
	ds_read_b128 v[192:195], v88 offset:24576
	s_waitcnt lgkmcnt(11)
	v_mfma_f32_32x32x16_bf16 v[138:153], v[98:101], v[10:13], 0
	ds_read_b128 v[98:101], v82 offset:24576
	v_exp_f32_e32 v154, v154
	v_exp_f32_e32 v155, v155
	s_waitcnt lgkmcnt(11)
	v_mfma_f32_32x32x16_bf16 v[138:153], v[102:105], v[14:17], v[138:153]
	ds_read_b128 v[102:105], v83 offset:24576
	v_exp_f32_e32 v156, v156
	v_exp_f32_e32 v157, v157
	s_waitcnt lgkmcnt(11)
	v_mfma_f32_32x32x16_bf16 v[18:33], v[196:199], v[118:121], v[18:33]
	v_exp_f32_e32 v158, v158
	v_exp_f32_e32 v159, v159
	s_waitcnt lgkmcnt(10)
	v_mfma_f32_32x32x16_bf16 v[34:49], v[216:219], v[118:121], v[34:49]
	v_exp_f32_e32 v160, v160
	v_exp_f32_e32 v161, v161
	s_waitcnt lgkmcnt(9)
	v_mfma_f32_32x32x16_bf16 v[50:65], v[200:203], v[118:121], v[50:65]
	v_add_f32_e32 v122, v154, v122
	v_add_f32_e32 v122, v155, v122
	v_add_f32_e32 v122, v156, v122
	v_add_f32_e32 v122, v157, v122
	s_waitcnt lgkmcnt(8)
	v_mfma_f32_32x32x16_bf16 v[66:81], v[204:207], v[118:121], v[66:81]
	v_add_f32_e32 v122, v158, v122
	v_add_f32_e32 v122, v159, v122
	v_add_f32_e32 v122, v160, v122
	v_add_f32_e32 v122, v161, v122
	v_cvt_pk_bf16_f32 v114, v154, v155
	v_cvt_pk_bf16_f32 v115, v156, v157
	v_cvt_pk_bf16_f32 v116, v158, v159
	v_cvt_pk_bf16_f32 v117, v160, v161
	ds_read_b128 v[196:199], v89 offset:0
	ds_read_b128 v[216:219], v89 offset:8192
	ds_read_b128 v[200:203], v89 offset:16384
	ds_read_b128 v[204:207], v89 offset:24576
	s_waitcnt lgkmcnt(11)
	v_mfma_f32_32x32x16_bf16 v[138:153], v[106:109], v[2:5], v[138:153]
	ds_read_b128 v[106:109], v84 offset:24576
	v_exp_f32_e32 v162, v162
	v_exp_f32_e32 v163, v163
	s_waitcnt lgkmcnt(11)
	v_mfma_f32_32x32x16_bf16 v[138:153], v[110:113], v[6:9], v[138:153]
	ds_read_b128 v[110:113], v85 offset:24576
	v_exp_f32_e32 v164, v164
	v_exp_f32_e32 v165, v165
	s_waitcnt lgkmcnt(11)
	v_mfma_f32_32x32x16_bf16 v[18:33], v[128:131], v[114:117], v[18:33]
	v_exp_f32_e32 v166, v166
	v_exp_f32_e32 v167, v167
	s_waitcnt lgkmcnt(10)
	v_mfma_f32_32x32x16_bf16 v[34:49], v[184:187], v[114:117], v[34:49]
	v_exp_f32_e32 v168, v168
	v_exp_f32_e32 v169, v169
	s_waitcnt lgkmcnt(9)
	v_mfma_f32_32x32x16_bf16 v[50:65], v[188:191], v[114:117], v[50:65]
	v_add_f32_e32 v122, v162, v122
	v_add_f32_e32 v122, v163, v122
	v_add_f32_e32 v122, v164, v122
	v_add_f32_e32 v122, v165, v122
	s_waitcnt lgkmcnt(8)
	v_mfma_f32_32x32x16_bf16 v[66:81], v[192:195], v[114:117], v[66:81]
	v_add_f32_e32 v122, v166, v122
	v_add_f32_e32 v122, v167, v122
	v_add_f32_e32 v122, v168, v122
	v_add_f32_e32 v122, v169, v122
	v_cvt_pk_bf16_f32 v118, v162, v163
	v_cvt_pk_bf16_f32 v119, v164, v165
	v_cvt_pk_bf16_f32 v120, v166, v167
	v_cvt_pk_bf16_f32 v121, v168, v169
	ds_read_b128 v[128:131], v90 offset:0
	ds_read_b128 v[184:187], v90 offset:8192
	ds_read_b128 v[188:191], v90 offset:16384
	ds_read_b128 v[192:195], v90 offset:24576
	s_waitcnt lgkmcnt(11)
	v_mfma_f32_32x32x16_bf16 v[154:169], v[98:101], v[10:13], 0
	v_exp_f32_e32 v138, v138
	v_exp_f32_e32 v139, v139
	s_waitcnt lgkmcnt(10)
	v_mfma_f32_32x32x16_bf16 v[154:169], v[102:105], v[14:17], v[154:169]
	v_exp_f32_e32 v140, v140
	v_exp_f32_e32 v141, v141
	s_waitcnt lgkmcnt(9)
	v_mfma_f32_32x32x16_bf16 v[18:33], v[196:199], v[118:121], v[18:33]
	v_exp_f32_e32 v142, v142
	v_exp_f32_e32 v143, v143
	s_waitcnt lgkmcnt(8)
	v_mfma_f32_32x32x16_bf16 v[34:49], v[216:219], v[118:121], v[34:49]
	v_exp_f32_e32 v144, v144
	v_exp_f32_e32 v145, v145
	s_waitcnt lgkmcnt(7)
	v_mfma_f32_32x32x16_bf16 v[50:65], v[200:203], v[118:121], v[50:65]
	v_add_f32_e32 v122, v138, v122
	v_add_f32_e32 v122, v139, v122
	v_add_f32_e32 v122, v140, v122
	v_add_f32_e32 v122, v141, v122
	s_waitcnt lgkmcnt(6)
	v_mfma_f32_32x32x16_bf16 v[66:81], v[204:207], v[118:121], v[66:81]
	v_add_f32_e32 v122, v142, v122
	v_add_f32_e32 v122, v143, v122
	v_add_f32_e32 v122, v144, v122
	v_add_f32_e32 v122, v145, v122
	v_cvt_pk_bf16_f32 v114, v138, v139
	v_cvt_pk_bf16_f32 v115, v140, v141
	v_cvt_pk_bf16_f32 v116, v142, v143
	v_cvt_pk_bf16_f32 v117, v144, v145
	ds_read_b128 v[196:199], v91 offset:0
	ds_read_b128 v[216:219], v91 offset:8192
	ds_read_b128 v[200:203], v91 offset:16384
	ds_read_b128 v[204:207], v91 offset:24576
	s_waitcnt lgkmcnt(9)
	v_mfma_f32_32x32x16_bf16 v[154:169], v[106:109], v[2:5], v[154:169]
	v_exp_f32_e32 v146, v146
	v_exp_f32_e32 v147, v147
	s_waitcnt lgkmcnt(8)
	v_mfma_f32_32x32x16_bf16 v[154:169], v[110:113], v[6:9], v[154:169]
	v_exp_f32_e32 v148, v148
	v_exp_f32_e32 v149, v149
	s_waitcnt lgkmcnt(7)
	v_mfma_f32_32x32x16_bf16 v[18:33], v[128:131], v[114:117], v[18:33]
	v_exp_f32_e32 v150, v150
	v_exp_f32_e32 v151, v151
	s_waitcnt lgkmcnt(6)
	v_mfma_f32_32x32x16_bf16 v[34:49], v[184:187], v[114:117], v[34:49]
	v_exp_f32_e32 v152, v152
	v_exp_f32_e32 v153, v153
	s_waitcnt lgkmcnt(5)
	v_mfma_f32_32x32x16_bf16 v[50:65], v[188:191], v[114:117], v[50:65]
	v_add_f32_e32 v122, v146, v122
	v_add_f32_e32 v122, v147, v122
	v_add_f32_e32 v122, v148, v122
	v_add_f32_e32 v122, v149, v122
	s_waitcnt lgkmcnt(4)
	v_mfma_f32_32x32x16_bf16 v[66:81], v[192:195], v[114:117], v[66:81]
	v_add_f32_e32 v122, v150, v122
	v_add_f32_e32 v122, v151, v122
	v_add_f32_e32 v122, v152, v122
	v_add_f32_e32 v122, v153, v122
	v_cvt_pk_bf16_f32 v118, v146, v147
	v_cvt_pk_bf16_f32 v119, v148, v149
	v_cvt_pk_bf16_f32 v120, v150, v151
	v_cvt_pk_bf16_f32 v121, v152, v153
	ds_read_b128 v[128:131], v92 offset:0
	ds_read_b128 v[184:187], v92 offset:8192
	ds_read_b128 v[188:191], v92 offset:16384
	ds_read_b128 v[192:195], v92 offset:24576
	s_waitcnt lgkmcnt(7)
	v_mfma_f32_32x32x16_bf16 v[18:33], v[196:199], v[118:121], v[18:33]
	v_exp_f32_e32 v154, v154
	v_exp_f32_e32 v155, v155
	v_exp_f32_e32 v156, v156
	s_waitcnt lgkmcnt(6)
	v_mfma_f32_32x32x16_bf16 v[34:49], v[216:219], v[118:121], v[34:49]
	v_exp_f32_e32 v157, v157
	v_exp_f32_e32 v158, v158
	v_exp_f32_e32 v159, v159
	v_exp_f32_e32 v160, v160
	s_waitcnt lgkmcnt(5)
	v_mfma_f32_32x32x16_bf16 v[50:65], v[200:203], v[118:121], v[50:65]
	v_exp_f32_e32 v161, v161
	v_add_f32_e32 v122, v154, v122
	v_add_f32_e32 v122, v155, v122
	v_add_f32_e32 v122, v156, v122
	v_add_f32_e32 v122, v157, v122
	v_add_f32_e32 v122, v158, v122
	s_waitcnt lgkmcnt(4)
	v_mfma_f32_32x32x16_bf16 v[66:81], v[204:207], v[118:121], v[66:81]
	v_add_f32_e32 v122, v159, v122
	v_add_f32_e32 v122, v160, v122
	v_add_f32_e32 v122, v161, v122
	v_xor_b32_e32 v82, 0x8000, v82
	v_xor_b32_e32 v83, 0x8000, v83
	v_xor_b32_e32 v84, 0x8000, v84
	v_xor_b32_e32 v85, 0x8000, v85
	v_cvt_pk_bf16_f32 v114, v154, v155
	v_cvt_pk_bf16_f32 v115, v156, v157
	v_cvt_pk_bf16_f32 v116, v158, v159
	v_cvt_pk_bf16_f32 v117, v160, v161
	ds_read_b128 v[196:199], v93 offset:0
	ds_read_b128 v[216:219], v93 offset:8192
	ds_read_b128 v[200:203], v93 offset:16384
	ds_read_b128 v[204:207], v93 offset:24576
	s_waitcnt lgkmcnt(7)
	v_mfma_f32_32x32x16_bf16 v[18:33], v[128:131], v[114:117], v[18:33]
	v_exp_f32_e32 v162, v162
	v_exp_f32_e32 v163, v163
	v_exp_f32_e32 v164, v164
	s_waitcnt lgkmcnt(6)
	v_mfma_f32_32x32x16_bf16 v[34:49], v[184:187], v[114:117], v[34:49]
	v_exp_f32_e32 v165, v165
	v_exp_f32_e32 v166, v166
	v_exp_f32_e32 v167, v167
	s_waitcnt lgkmcnt(5)
	v_mfma_f32_32x32x16_bf16 v[50:65], v[188:191], v[114:117], v[50:65]
	v_exp_f32_e32 v168, v168
	v_exp_f32_e32 v169, v169
	v_add_f32_e32 v122, v162, v122
	v_add_f32_e32 v122, v163, v122
	s_waitcnt lgkmcnt(4)
	v_mfma_f32_32x32x16_bf16 v[66:81], v[192:195], v[114:117], v[66:81]
	v_add_f32_e32 v122, v164, v122
	v_add_f32_e32 v122, v165, v122
	v_add_f32_e32 v122, v166, v122
	v_add_f32_e32 v122, v167, v122
	v_add_f32_e32 v122, v168, v122
	v_add_f32_e32 v122, v169, v122
	v_cvt_pk_bf16_f32 v118, v162, v163
	v_cvt_pk_bf16_f32 v119, v164, v165
	v_cvt_pk_bf16_f32 v120, v166, v167
	v_cvt_pk_bf16_f32 v121, v168, v169
	s_waitcnt lgkmcnt(3)
	s_nop 0
	v_mfma_f32_32x32x16_bf16 v[18:33], v[196:199], v[118:121], v[18:33]
	v_xor_b32_e32 v86, 0x8000, v86
	v_xor_b32_e32 v87, 0x8000, v87
	s_waitcnt lgkmcnt(2)
	v_mfma_f32_32x32x16_bf16 v[34:49], v[216:219], v[118:121], v[34:49]
	v_xor_b32_e32 v88, 0x8000, v88
	v_xor_b32_e32 v89, 0x8000, v89
	s_waitcnt lgkmcnt(1)
	v_mfma_f32_32x32x16_bf16 v[50:65], v[200:203], v[118:121], v[50:65]
	v_xor_b32_e32 v90, 0x8000, v90
	v_xor_b32_e32 v91, 0x8000, v91
	s_waitcnt lgkmcnt(0)
	v_mfma_f32_32x32x16_bf16 v[66:81], v[204:207], v[118:121], v[66:81]
	v_xor_b32_e32 v92, 0x8000, v92
	v_xor_b32_e32 v93, 0x8000, v93
	s_waitcnt vmcnt(0)
	s_waitcnt lgkmcnt(0)
	s_barrier
	s_add_i32 s15, s15, 1
	s_cmp_eq_u32 s15, 34
	s_cbranch_scc0 .Lattn_nf_loop
	v_readlane_b32 s64, v175, 0
	v_readlane_b32 s65, v175, 1
	v_readlane_b32 s66, v175, 2
	v_readlane_b32 s67, v175, 3
	v_readlane_b32 s68, v175, 4
	v_readlane_b32 s69, v175, 5
	v_readlane_b32 s70, v175, 6
	v_readlane_b32 s71, v175, 7
	v_readlane_b32 s72, v175, 8
	v_readlane_b32 s73, v175, 9
	v_readlane_b32 s74, v175, 10
	v_readlane_b32 s75, v175, 11
	v_readlane_b32 s76, v175, 12
	v_readlane_b32 s77, v175, 13
	v_readlane_b32 s78, v175, 14
	v_readlane_b32 s79, v175, 15
	s_nop 4
	s_mov_b32 s10, 0x3fb8aa3b
	s_mov_b32 s11, 0xc2ce8ed0
	s_mov_b32 s6, 0x42b17218
	v_cmp_eq_u32_e64 s[40:41], 0, v179
	s_lshl_b32 s30, s14, 1
	v_lshlrev_b32_e32 v196, 3, v178
	v_mov_b32_e32 v197, 0
	v_lshlrev_b32_e32 v198, 4, v179
	v_or3_b32 v198, v198, v177, v180
	v_ashrrev_i32_e32 v199, 31, v198
	v_lshlrev_b64 v[198:199], 11, v[198:199]
	s_mov_b64 s[100:101], 0x18a10000
	v_lshl_add_u64 v[198:199], s[42:43], 0, v[198:199]
	v_lshl_add_u64 v[198:199], v[198:199], 0, s[30:31]
	v_lshl_add_u64 v[198:199], v[198:199], 0, v[196:197]
	v_lshl_add_u64 v[198:199], v[198:199], 0, s[100:101]
	global_load_dwordx2 v[146:147], v[198:199], off
	global_load_dwordx2 v[148:149], v[198:199], off offset:32
	global_load_dwordx2 v[150:151], v[198:199], off offset:64
	global_load_dwordx2 v[152:153], v[198:199], off offset:96
	global_load_dwordx2 v[188:189], v[198:199], off offset:128
	global_load_dwordx2 v[190:191], v[198:199], off offset:160
	global_load_dwordx2 v[192:193], v[198:199], off offset:192
	global_load_dwordx2 v[194:195], v[198:199], off offset:224
	s_mov_b64 s[100:101], exec
	s_and_b64 exec, exec, s[4:5]
	s_cbranch_execz .Lpop_skip
	v_readlane_b32 s14, v255, 22
	v_readlane_b32 s15, v255, 23
	v_mov_b32_e32 v224, 1
	s_nop 4
	global_atomic_add v224, v0, v224, s[14:15] sc0
